# GLA scan: Qd/Ki tiles stored k-permuted so Qd fragments are single b128 reads; Qd and KiT fragment reads issued ahead of their MFMAs
# speedup vs baseline: 1.0256x; 1.0054x over previous
; template <int VAR> __device__ __forceinline__ void gla_chunk_item(const Frame& F, int item, bool last) {
;     ...
;             unsigned kt0[8], kt1[8];
;             const unsigned a_pq = opq(G_QD + ((16 * qt) * GQ_LD + 2 * dp) * 2);
;             const unsigned a_pkt = opq(G_KT + ((2 * dp) * GT_LD + 16 * qt) * 2);
;         const unsigned a_pvt = opq(G_VT + (jj * GV_LD + 8 * e8) * 2);
; #pragma unroll
;             for (int i = 0; i < 16; ++i) {
;                 o0 += bflo(rl[i]); o1 += bfhi(rl[i]);
;                 const float e0 = fexp(o0), e1 = fexp(o1), n0 = fexp(-o0), n1 = fexp(-o1);
;                 const unsigned qd = pg8::cvt_pk_bf16(bflo(rq[i]) * 0.0625f * e0, bfhi(rq[i]) * 0.0625f * e1);
;                 const unsigned ki = pg8::cvt_pk_bf16(bflo(rk[i]) * n0, bfhi(rk[i]) * n1);
;                 ST_(unsigned, a_pq + i * GQ_LD * 2) = qd;
;                 ST_(unsigned, a_pq + (G_KI - G_QD) + i * GQ_LD * 2) = ki;
;                 if (i & 1) { kt0[i >> 1] |= (ki << 16); kt1[i >> 1] |= (ki & 0xffff0000u); }
;                 else { kt0[i >> 1] = ki & 0xffffu; kt1[i >> 1] = ki >> 16; }
;                 asm volatile("" ::: "memory");
;             }
;             ST_(v4u, a_pkt) = (v4u){kt0[0], kt0[1], kt0[2], kt0[3]};
;             ST_(v4u, a_pkt + 16) = (v4u){kt0[4], kt0[5], kt0[6], kt0[7]};
;             ST_(v4u, a_pkt + GT_LD * 2) = (v4u){kt1[0], kt1[1], kt1[2], kt1[3]};
;             ST_(v4u, a_pkt + GT_LD * 2 + 16) = (v4u){kt1[4], kt1[5], kt1[6], kt1[7]};
;             ST_(v4u, a_pvt) = rv0; ST_(v4u, a_pvt + 32 * GV_LD * 2) = rv1;
;         }
;         __syncthreads();
;         if (chunk + 1 < 36 && VAR != 1) GLA_ISSUE(chunk + 1);
;         const unsigned a_f8 = opq((l16 * GQ_LD + 8 * g) * 2);
; #pragma unroll
;         for (int tt = 0; tt < 2; ++tt) {
;             const int t = 2 * w + tt, jt = t >> 2, it = t & 3;
;             f32x4 acc = (f32x4){0.f, 0.f, 0.f, 0.f};
;             if (jt <= it) {
;                 const unsigned ak = a_f8 + G_KI + jt * (16 * GQ_LD * 2), aq = a_f8 + G_QD + it * (16 * GQ_LD * 2);
; #pragma unroll
;                 for (int s = 0; s < 8; ++s) {
;                     const bf16x8 a = LD_(bf16x8, ak + 64 * s);
;                     const bf16x8 bb = LD_(bf16x8, aq + 64 * s);
;                     acc = __builtin_amdgcn_mfma_f32_16x16x32_bf16(a, bb, acc, 0, 0, 0);
;                 }
;             }
.LBB0_802:
	v_lshlrev_b32_e32 v0, 1, v165
	v_and_b32_e32 v4, 0xfe, v0
	v_lshlrev_b32_e32 v5, 2, v4
	v_ashrrev_i32_e32 v3, 7, v165
	v_or_b32_e32 v159, 0x20800, v5
	v_add_u32_e32 v5, 0, v5
	s_movk_i32 s8, 0x1080
	v_add_u32_e32 v160, 0x20400, v5
	v_mul_lo_u32 v5, v3, s8
	v_and_b32_e32 v6, 0xe3, v4
	v_and_b32_e32 v9, 12, v4
	v_lshl_or_b32 v6, v9, 1, v6
	v_bfe_u32 v9, v4, 4, 1
	v_lshl_or_b32 v6, v9, 2, v6
	v_add_lshl_u32 v161, v5, v6, 1
	v_lshlrev_b32_e32 v5, 5, v3
	v_mul_u32_u24_e32 v7, 0x90, v4
	s_mov_b32 s8, 0x10800
	v_ashrrev_i32_e32 v158, 4, v165
	v_add3_u32 v162, v5, v7, s8
	s_movk_i32 s8, 0x88
	v_lshlrev_b32_e32 v7, 3, v185
	s_movk_i32 s9, 0x108
	v_and_b32_e32 v6, 0x78, v167
	v_mul_lo_u32 v5, v158, s8
	v_mad_u32_u24 v8, v104, s9, v7
	s_mov_b32 s75, s11
	v_add_lshl_u32 v5, v5, v6, 1
	v_lshlrev_b32_e32 v166, 1, v8
	v_add_u32_e32 v10, s63, v188
	s_waitcnt vmcnt(8)
	v_mad_u32_u24 v168, v104, s9, v8
	v_mul_i32_i24_e32 v8, 0xfffffe38, v104
	v_readlane_b32 s10, v255, 45
	v_readlane_b32 s76, v255, 49
	v_add_u32_e32 v164, 0x19800, v5
	v_or_b32_e32 v11, 2, v10
	v_or_b32_e32 v12, 3, v10
	v_add_lshl_u32 v169, v168, v8, 1
	v_or_b32_e32 v7, v7, v186
	v_or_b32_e32 v8, s10, v184
	v_add_u32_e32 v173, 0x8400, v5
	v_readlane_b32 s16, v255, 47
	v_or_b32_e32 v5, s62, v104
	s_movk_i32 s34, 0x48
	v_readlane_b32 s86, v255, 8
	v_readlane_b32 s77, v255, 50
	s_add_u32 s33, s76, 0x51c00000
	v_mad_u64_u32 v[8:9], s[8:9], v7, s8, v[8:9]
	s_mul_i32 s53, s16, 0x2100
	v_cmp_gt_i32_e64 s[16:17], v10, v5
	v_cmp_lt_i32_e64 s[18:19], v10, v5
	v_cmp_gt_i32_e64 s[20:21], v11, v5
	v_cmp_gt_i32_e64 s[22:23], v12, v5
	v_mad_u32_u24 v5, v5, s34, v10
	v_readlane_b32 s87, v255, 9
	s_addc_u32 s50, s77, 0
	v_mov_b32_e32 v7, 0x19800
	s_movk_i32 s8, 0x220
	v_lshl_add_u32 v5, v5, 1, 0
	s_load_dwordx4 s[88:91], s[86:87], 0xf0
	s_add_u32 s0, s76, 0x2e100000
	v_lshl_add_u32 v171, v8, 1, v7
	v_mul_lo_u32 v7, v185, s8
	v_add_u32_e32 v174, 0x1e000, v5
	v_or_b32_e32 v5, s74, v104
	s_addc_u32 s1, s77, 0
	v_add_u32_e32 v7, s10, v7
	v_cmp_gt_i32_e64 s[24:25], v10, v5
	v_cmp_lt_i32_e64 s[26:27], v10, v5
	v_cmp_gt_i32_e64 s[28:29], v11, v5
	v_cmp_gt_i32_e64 s[30:31], v12, v5
	v_mad_u32_u24 v5, v5, s34, v10
	s_add_u32 s51, s76, 0x3b900000
	v_lshlrev_b32_e32 v0, 1, v4
	v_mov_b32_e32 v1, v2
	s_movk_i32 s6, 0x80
	v_readlane_b32 s11, v255, 46
	v_or_b32_e32 v7, v7, v104
	v_mov_b32_e32 v8, 0x8400
	v_lshl_add_u32 v5, v5, 1, 0
	v_readlane_b32 s82, v255, 52
	s_addc_u32 s52, s77, 0
	v_lshl_add_u64 v[0:1], s[0:1], 0, v[0:1]
	v_cmp_gt_u32_e64 s[6:7], s6, v165
	v_add_u32_e32 v170, 0x20400, v187
	v_lshl_add_u32 v172, v7, 1, v8
	v_cmp_lt_i32_e64 s[8:9], 0, v3
	v_cmp_lt_i32_e64 s[10:11], 1, v3
	v_cmp_lt_i32_e64 s[12:13], 2, v3
	v_cmp_lt_i32_e64 s[14:15], 3, v3
	v_add_u32_e32 v175, 0x1e000, v5
	v_lshlrev_b32_e32 v148, 1, v4
	v_lshlrev_b32_e32 v150, 1, v6
	s_mov_b32 s54, s82
	v_readlane_b32 s92, v255, 10
	v_readlane_b32 s93, v255, 11
	s_movk_i32 s71, 0x1000
	s_mov_b32 s73, 0xf800000
	s_movk_i32 s83, 0x3000
	s_mov_b32 s74, 0xffff0000
	s_branch .LBB0_804

; __device__ __forceinline__ unsigned cvt_pk_bf16(float lo, float hi) { const f2_t_ v = {lo, hi}; return __builtin_bit_cast(unsigned, __builtin_convertvector(v, bf2_t_)); }
; __device__ __forceinline__ unsigned opq(unsigned x) { asm volatile("" : "+v"(x)); return x; }
; template <int VAR> __device__ __forceinline__ void gla_chunk_item(const Frame& F, int item, bool last) {
;     ...
;             const int i = 16 * it + l16, j0 = 16 * jt + 4 * g;
;             const float m0 = (j0 + 0 <= i) ? acc[0] : 0.f, m1 = (j0 + 1 <= i) ? acc[1] : 0.f, m2 = (j0 + 2 <= i) ? acc[2] : 0.f, m3 = (j0 + 3 <= i) ? acc[3] : 0.f;
;             ST_(v2u, G_AM + (i * GT_LD + j0) * 2) = (v2u){pg8::cvt_pk_bf16(m0, m1), pg8::cvt_pk_bf16(m2, m3)};
;         }
;         __syncthreads();
;         if (VAR != 3)
;         {
;             const unsigned a_f4 = opq(G_QD + (l16 * GQ_LD + 4 * g) * 2), a_t8 = opq((l16 * GT_LD + 8 * g) * 2), a_ebl = opq(G_EBL + 16 * g);
;             const unsigned a_vtr = opq(G_VT + ((8 * g + (l16 >> 2)) * GV_LD + 16 * w + 4 * (l16 & 3)) * 2);
;             const unsigned a_os = opq(G_KI + ((4 * g) * GV_LD + 16 * w + l16) * 2);
;             f32x4 O[4];
; #pragma unroll
;             for (int mt = 0; mt < 4; ++mt) O[mt] = (f32x4){0.f, 0.f, 0.f, 0.f};
; #pragma unroll
;             for (int s = 0; s < 8; ++s) {
;                 const bf16x8 bs = pack8(S[2 * s], S[2 * s + 1]);
; #pragma unroll
;                 for (int mt = 0; mt < 4; ++mt) {
;                     const v2u a0 = LD_(v2u, a_f4 + (16 * mt * GQ_LD + 32 * s) * 2);
;                     const v2u a1 = LD_(v2u, a_f4 + (16 * mt * GQ_LD + 32 * s + 16) * 2);
;                     const bf16x8 a = __builtin_bit_cast(bf16x8, (v4u){a0.x, a0.y, a1.x, a1.y});
;                     O[mt] = __builtin_amdgcn_mfma_f32_16x16x32_bf16(a, bs, O[mt], 0, 0, 0);
;                 }
;                 asm volatile("" ::: "memory");
;             }
.LBB0_818:
	s_nop 7
	v_cndmask_b32_e64 v76, v76, 0, s[24:25]
	v_cndmask_b32_e64 v77, 0, v77, s[26:27]
	v_cndmask_b32_e64 v78, v78, 0, s[28:29]
	v_cndmask_b32_e64 v79, v79, 0, s[30:31]
	v_cvt_pk_bf16_f32 v76, v76, v77
	v_cvt_pk_bf16_f32 v77, v78, v79
	ds_write_b64 v175, v[76:77]
	v_mov_b32_e32 v77, v166
	s_waitcnt lgkmcnt(0)
	s_barrier
	v_mov_b32_e32 v84, v169
	v_mov_b32_e32 v100, v170
	v_mov_b32_e32 v76, v171
	v_mov_b32_e32 v101, v172
	v_add_u32_e32 v77, 0, v77
	ds_read_b128 v[78:81], v77
	v_cvt_pk_bf16_f32 v86, v72, v73
	v_cvt_pk_bf16_f32 v87, v74, v75
	v_cvt_pk_bf16_f32 v88, v68, v69
	v_cvt_pk_bf16_f32 v89, v70, v71
	v_add_u32_e32 v149, 0, v84
	v_add_u32_e32 v84, 0x1e000, v149
	s_waitcnt lgkmcnt(0)
	v_mfma_f32_16x16x32_bf16 v[90:93], v[78:81], v[86:89], 0
	v_add_u32_e32 v78, 0x2000, v77
	ds_read_b128 v[80:83], v78 offset:256
	v_add_u32_e32 v79, 0x4000, v77
	s_waitcnt lgkmcnt(0)
	v_mfma_f32_16x16x32_bf16 v[94:97], v[80:83], v[86:89], 0
	ds_read_b128 v[80:83], v79 offset:512
	s_and_b64 s[48:49], s[84:85], s[46:47]
	s_xor_b64 s[46:47], s[48:49], -1
	s_waitcnt lgkmcnt(0)
	v_mfma_f32_16x16x32_bf16 v[102:105], v[80:83], v[86:89], 0
	v_add_u32_e32 v80, 0x6000, v77
	ds_read_b128 v[106:109], v80 offset:768
	ds_read_b128 v[110:113], v77 offset:64
	ds_read_b128 v[198:201], v78 offset:320
	ds_read_b128 v[228:231], v79 offset:576
	s_waitcnt lgkmcnt(3)
	v_mfma_f32_16x16x32_bf16 v[86:89], v[106:109], v[86:89], 0
	v_cvt_pk_bf16_f32 v106, v64, v65
	v_cvt_pk_bf16_f32 v107, v66, v67
	v_cvt_pk_bf16_f32 v108, v60, v61
	v_cvt_pk_bf16_f32 v109, v62, v63
	s_and_b64 vcc, exec, s[48:49]
	s_waitcnt lgkmcnt(2)
	s_nop 0
	v_mfma_f32_16x16x32_bf16 v[90:93], v[110:113], v[106:109], v[90:93]
	ds_read_b128 v[110:113], v80 offset:832
	s_waitcnt lgkmcnt(2)
	v_mfma_f32_16x16x32_bf16 v[94:97], v[198:201], v[106:109], v[94:97]
	ds_read_b128 v[198:201], v77 offset:128
	s_waitcnt lgkmcnt(2)
	v_mfma_f32_16x16x32_bf16 v[102:105], v[228:231], v[106:109], v[102:105]
	ds_read_b128 v[228:231], v78 offset:384
	s_waitcnt lgkmcnt(2)
	v_mfma_f32_16x16x32_bf16 v[86:89], v[110:113], v[106:109], v[86:89]
	ds_read_b128 v[110:113], v79 offset:640
	v_cvt_pk_bf16_f32 v106, v56, v57
	v_cvt_pk_bf16_f32 v107, v58, v59
	v_cvt_pk_bf16_f32 v108, v52, v53
	v_cvt_pk_bf16_f32 v109, v54, v55
	s_waitcnt lgkmcnt(2)
	s_nop 0
	v_mfma_f32_16x16x32_bf16 v[90:93], v[198:201], v[106:109], v[90:93]
	ds_read_b128 v[198:201], v80 offset:896
	s_waitcnt lgkmcnt(2)
	v_mfma_f32_16x16x32_bf16 v[94:97], v[228:231], v[106:109], v[94:97]
	ds_read_b128 v[228:231], v77 offset:192
	s_waitcnt lgkmcnt(2)
	v_mfma_f32_16x16x32_bf16 v[102:105], v[110:113], v[106:109], v[102:105]
	ds_read_b128 v[110:113], v78 offset:448
	s_waitcnt lgkmcnt(2)
	v_mfma_f32_16x16x32_bf16 v[86:89], v[198:201], v[106:109], v[86:89]
	ds_read_b128 v[198:201], v79 offset:704
	v_cvt_pk_bf16_f32 v106, v48, v49
	v_cvt_pk_bf16_f32 v107, v50, v51
	v_cvt_pk_bf16_f32 v108, v44, v45
	v_cvt_pk_bf16_f32 v109, v46, v47
	s_waitcnt lgkmcnt(2)
	s_nop 0
	v_mfma_f32_16x16x32_bf16 v[90:93], v[228:231], v[106:109], v[90:93]
	ds_read_b128 v[228:231], v80 offset:960
	s_waitcnt lgkmcnt(2)
	v_mfma_f32_16x16x32_bf16 v[94:97], v[110:113], v[106:109], v[94:97]
	ds_read_b128 v[110:113], v77 offset:256
	s_waitcnt lgkmcnt(2)
	v_mfma_f32_16x16x32_bf16 v[102:105], v[198:201], v[106:109], v[102:105]
	ds_read_b128 v[198:201], v78 offset:512
	s_waitcnt lgkmcnt(2)
	v_mfma_f32_16x16x32_bf16 v[86:89], v[228:231], v[106:109], v[86:89]
	ds_read_b128 v[228:231], v79 offset:768
	v_cvt_pk_bf16_f32 v106, v40, v41
	v_cvt_pk_bf16_f32 v107, v42, v43
	v_cvt_pk_bf16_f32 v108, v36, v37
	v_cvt_pk_bf16_f32 v109, v38, v39
	s_waitcnt lgkmcnt(2)
	s_nop 0
	v_mfma_f32_16x16x32_bf16 v[90:93], v[110:113], v[106:109], v[90:93]
	ds_read_b128 v[110:113], v80 offset:1024
	s_waitcnt lgkmcnt(2)
	v_mfma_f32_16x16x32_bf16 v[94:97], v[198:201], v[106:109], v[94:97]
	ds_read_b128 v[198:201], v77 offset:320
	s_waitcnt lgkmcnt(2)
	v_mfma_f32_16x16x32_bf16 v[102:105], v[228:231], v[106:109], v[102:105]
	ds_read_b128 v[228:231], v78 offset:576
	s_waitcnt lgkmcnt(2)
	v_mfma_f32_16x16x32_bf16 v[86:89], v[110:113], v[106:109], v[86:89]
	ds_read_b128 v[110:113], v79 offset:832
	v_cvt_pk_bf16_f32 v106, v32, v33
	v_cvt_pk_bf16_f32 v107, v34, v35
	v_cvt_pk_bf16_f32 v108, v28, v29
	v_cvt_pk_bf16_f32 v109, v30, v31
	s_waitcnt lgkmcnt(2)
	s_nop 0
	v_mfma_f32_16x16x32_bf16 v[90:93], v[198:201], v[106:109], v[90:93]
	ds_read_b128 v[198:201], v80 offset:1088
	s_waitcnt lgkmcnt(2)
	v_mfma_f32_16x16x32_bf16 v[94:97], v[228:231], v[106:109], v[94:97]
	ds_read_b128 v[228:231], v77 offset:384
	s_waitcnt lgkmcnt(2)
	v_mfma_f32_16x16x32_bf16 v[102:105], v[110:113], v[106:109], v[102:105]
	ds_read_b128 v[110:113], v78 offset:640
	s_waitcnt lgkmcnt(2)
	v_mfma_f32_16x16x32_bf16 v[86:89], v[198:201], v[106:109], v[86:89]
	ds_read_b128 v[198:201], v79 offset:896
	v_cvt_pk_bf16_f32 v106, v24, v25
	v_cvt_pk_bf16_f32 v107, v26, v27
	v_cvt_pk_bf16_f32 v108, v20, v21
	v_cvt_pk_bf16_f32 v109, v22, v23
	s_waitcnt lgkmcnt(2)
	s_nop 0
	v_mfma_f32_16x16x32_bf16 v[90:93], v[228:231], v[106:109], v[90:93]
	ds_read_b128 v[228:231], v80 offset:1152
	s_waitcnt lgkmcnt(2)
	v_mfma_f32_16x16x32_bf16 v[94:97], v[110:113], v[106:109], v[94:97]
	ds_read_b128 v[110:113], v77 offset:448
	s_waitcnt lgkmcnt(2)
	v_mfma_f32_16x16x32_bf16 v[102:105], v[198:201], v[106:109], v[102:105]
	ds_read_b128 v[198:201], v78 offset:704
	s_waitcnt lgkmcnt(2)
	v_mfma_f32_16x16x32_bf16 v[86:89], v[228:231], v[106:109], v[86:89]
	v_cvt_pk_bf16_f32 v106, v16, v17
	v_cvt_pk_bf16_f32 v107, v18, v19
	v_cvt_pk_bf16_f32 v108, v4, v5
	v_cvt_pk_bf16_f32 v109, v6, v7
	s_waitcnt lgkmcnt(1)
; __device__ __forceinline__ unsigned f2bf(float f) { return pk2(f, 0.f) & 0xffffu; }
; template <int VAR> __device__ __forceinline__ void gla_chunk_item(const Frame& F, int item, bool last) {
;     ...
;             for (int s = 0; s < 8; ++s) {
;                 const bf16x8 bs = pack8(S[2 * s], S[2 * s + 1]);
; #pragma unroll
;                 for (int mt = 0; mt < 4; ++mt) {
;                     const v2u a0 = LD_(v2u, a_f4 + (16 * mt * GQ_LD + 32 * s) * 2);
;                     const v2u a1 = LD_(v2u, a_f4 + (16 * mt * GQ_LD + 32 * s + 16) * 2);
;                     const bf16x8 a = __builtin_bit_cast(bf16x8, (v4u){a0.x, a0.y, a1.x, a1.y});
;                     O[mt] = __builtin_amdgcn_mfma_f32_16x16x32_bf16(a, bs, O[mt], 0, 0, 0);
;                 }
;                 asm volatile("" ::: "memory");
;             }
;             const bf16x8 vb0 = tr8(L, a_vtr, a_vtr + 4 * GV_LD * 2);
;             const bf16x8 vb1 = tr8(L, a_vtr + 32 * GV_LD * 2, a_vtr + 36 * GV_LD * 2);
; #pragma unroll
;             for (int mt = 0; mt < 4; ++mt) {
;                 const bf16x8 a0 = LD_(bf16x8, a_t8 + G_AM + mt * (16 * GT_LD * 2));
;                 O[mt] = __builtin_amdgcn_mfma_f32_16x16x32_bf16(a0, vb0, O[mt], 0, 0, 0);
;                 if (mt >= 2) { const bf16x8 a1 = LD_(bf16x8, a_t8 + G_AM + mt * (16 * GT_LD * 2) + 64);
;                     O[mt] = __builtin_amdgcn_mfma_f32_16x16x32_bf16(a1, vb1, O[mt], 0, 0, 0); }
;             }
;             if (VAR == 0 && !(last && chunk < 4)) {
;                 const unsigned aos = a_os;
; #pragma unroll
;                 for (int mt = 0; mt < 4; ++mt)
; #pragma unroll
;                     for (int r = 0; r < 4; ++r) ST_(unsigned short, aos + (16 * mt + r) * (GV_LD * 2)) = (unsigned short)f2bf(O[mt][r]);
;             }
	s_nop 0
	v_mfma_f32_16x16x32_bf16 v[90:93], v[110:113], v[106:109], v[90:93]
	s_waitcnt lgkmcnt(0)
	v_mfma_f32_16x16x32_bf16 v[94:97], v[198:201], v[106:109], v[94:97]
	ds_read_b128 v[110:113], v79 offset:960
	ds_read_b128 v[78:81], v80 offset:1216
	s_waitcnt lgkmcnt(1)
	v_mfma_f32_16x16x32_bf16 v[102:105], v[110:113], v[106:109], v[102:105]
	s_waitcnt lgkmcnt(0)
	v_mfma_f32_16x16x32_bf16 v[106:109], v[78:81], v[106:109], v[86:89]
	v_add_u32_e32 v78, 0, v76
	ds_read_b64_tr_b16 v[80:81], v78
	ds_read_b64_tr_b16 v[82:83], v78 offset:1088
	ds_read_b64_tr_b16 v[76:77], v78 offset:8704
	ds_read_b64_tr_b16 v[78:79], v78 offset:9792
	ds_read_b128 v[84:87], v84
	v_add_u32_e32 v88, 0x1e900, v149
	s_waitcnt lgkmcnt(0)
	v_mfma_f32_16x16x32_bf16 v[84:87], v[84:87], v[80:83], v[90:93]
	s_nop 2
	ds_read_b128 v[88:91], v88
	v_add_u32_e32 v92, 0x1f200, v149
	s_waitcnt lgkmcnt(0)
	v_mfma_f32_16x16x32_bf16 v[88:91], v[88:91], v[80:83], v[94:97]
	s_nop 2
	ds_read_b128 v[92:95], v92
	v_add_u32_e32 v96, 0x1f240, v149
	ds_read_b128 v[96:99], v96
	s_waitcnt lgkmcnt(1)
	v_mfma_f32_16x16x32_bf16 v[92:95], v[92:95], v[80:83], v[102:105]
	s_nop 2
	v_add_u32_e32 v102, 0x1fb40, v149
	ds_read_b128 v[102:105], v102
	s_waitcnt lgkmcnt(1)
	v_mfma_f32_16x16x32_bf16 v[92:95], v[96:99], v[76:79], v[92:95]
	v_add_u32_e32 v96, 0x1fb00, v149
	ds_read_b128 v[96:99], v96
	s_waitcnt lgkmcnt(0)
	v_mfma_f32_16x16x32_bf16 v[96:99], v[96:99], v[80:83], v[106:109]
	v_mfma_f32_16x16x32_bf16 v[96:99], v[102:105], v[76:79], v[96:99]
	s_cbranch_vccnz .LBB0_820
	v_add_u32_e32 v101, 0, v101
	v_cvt_pk_bf16_f32 v84, v84, s0
	ds_write_b16 v101, v84
	v_cvt_pk_bf16_f32 v84, v85, s0
	ds_write_b16 v101, v84 offset:272
	v_cvt_pk_bf16_f32 v84, v86, s0
	ds_write_b16 v101, v84 offset:544
	v_cvt_pk_bf16_f32 v84, v87, s0
	ds_write_b16 v101, v84 offset:816
	v_cvt_pk_bf16_f32 v84, v88, s0
	ds_write_b16 v101, v84 offset:4352
	v_cvt_pk_bf16_f32 v84, v89, s0
	ds_write_b16 v101, v84 offset:4624
	v_cvt_pk_bf16_f32 v84, v90, s0
	ds_write_b16 v101, v84 offset:4896
	v_cvt_pk_bf16_f32 v84, v91, s0
	ds_write_b16 v101, v84 offset:5168
	v_cvt_pk_bf16_f32 v84, v92, s0
	ds_write_b16 v101, v84 offset:8704
	v_cvt_pk_bf16_f32 v84, v93, s0
	ds_write_b16 v101, v84 offset:8976
	v_cvt_pk_bf16_f32 v84, v94, s0
	ds_write_b16 v101, v84 offset:9248
	v_cvt_pk_bf16_f32 v84, v95, s0
	ds_write_b16 v101, v84 offset:9520
	v_cvt_pk_bf16_f32 v84, v96, s0
	ds_write_b16 v101, v84 offset:13056
	v_cvt_pk_bf16_f32 v84, v97, s0
	ds_write_b16 v101, v84 offset:13328
	v_cvt_pk_bf16_f32 v84, v98, s0
	ds_write_b16 v101, v84 offset:13600
	v_cvt_pk_bf16_f32 v84, v99, s0
	ds_write_b16 v101, v84 offset:13872
; #define GAS __attribute__((address_space(1)))
; __device__ __forceinline__ unsigned opq(unsigned x) { asm volatile("" : "+v"(x)); return x; }
; template <int VAR> __device__ __forceinline__ void gla_chunk_item(const Frame& F, int item, bool last) {
;     ...
; #pragma unroll
;             for (int t = 0; t < 16; ++t) {
;                 const bf16x8 a0 = LD_(bf16x8, a_t8 + G_KT + t * (16 * GT_LD * 2));
;                 const bf16x8 a1 = LD_(bf16x8, a_t8 + G_KT + t * (16 * GT_LD * 2) + 64);
;                 S[t] = __builtin_amdgcn_mfma_f32_16x16x32_bf16(a0, vb0, S[t], 0, 0, 0);
;                 S[t] = __builtin_amdgcn_mfma_f32_16x16x32_bf16(a1, vb1, S[t], 0, 0, 0);
;                 const f32x4 eb = LD_(f32x4, a_ebl + 64 * t);
;                 S[t] = S[t] * eb;
;                 asm volatile("" ::: "memory");
;             }
;         }
;         __syncthreads();
;         if (VAR == 0 && !(last && chunk < 4)) {
;             const unsigned a_or = opq(G_KI + ((tid >> 4) * GV_LD + 8 * (tid & 15)) * 2);
;             const v4u o0 = LD_(v4u, a_or), o1 = LD_(v4u, a_or + 32 * GV_LD * 2);
;             GAS bf16* yp = (GAS bf16*)(YG + (size_t)(r0 + sgn * (tid >> 4)) * 2048 + h * 512 + dvs * 128 + 8 * (tid & 15));
;             *(GAS v4u*)yp = o0; *(GAS v4u*)(yp + (long)sgn * 32 * 2048) = o1;
;         }
.LBB0_820:
	v_add_u32_e32 v84, 0x10800, v149
	ds_read_b128 v[88:91], v84
	v_add_u32_e32 v84, 0x10840, v149
	v_add_u32_e32 v151, 0, v100
	s_nop 2
	v_add_u32_e32 v96, 0x11100, v149
	ds_read_b128 v[92:95], v84
	ds_read_b128 v[84:87], v151
	v_add_u32_e32 v100, 0x12340, v149
	v_add_u32_e32 v104, 0x12c40, v149
	v_add_u32_e32 v108, 0x13540, v149
	s_waitcnt lgkmcnt(2)
	v_mfma_f32_16x16x32_bf16 v[72:75], v[88:91], v[80:83], v[72:75]
	ds_read_b128 v[88:91], v96
	v_add_u32_e32 v112, 0x13e40, v149
	v_add_u32_e32 v116, 0x14740, v149
	v_add_u32_e32 v120, 0x15040, v149
	v_add_u32_e32 v124, 0x15940, v149
	v_add_u32_e32 v128, 0x16240, v149
	v_add_u32_e32 v132, 0x16b40, v149
	v_add_u32_e32 v136, 0x17440, v149
	s_waitcnt lgkmcnt(0)
	v_mfma_f32_16x16x32_bf16 v[96:99], v[88:91], v[80:83], v[68:71]
	v_add_u32_e32 v88, 0x11140, v149
	v_add_u32_e32 v140, 0x17d40, v149
	v_add_u32_e32 v144, 0x18640, v149
	v_mfma_f32_16x16x32_bf16 v[68:71], v[92:95], v[76:79], v[72:75]
	s_nop 2
	ds_read_b128 v[72:75], v88
	ds_read_b128 v[88:91], v151 offset:64
	s_andn2_b64 vcc, exec, s[46:47]
	s_waitcnt lgkmcnt(1)
	v_mfma_f32_16x16x32_bf16 v[92:95], v[72:75], v[76:79], v[96:99]
	v_add_u32_e32 v72, 0x11a00, v149
	ds_read_b128 v[72:75], v72
	s_nop 0
	v_add_u32_e32 v96, 0x11a40, v149
	s_waitcnt lgkmcnt(0)
	v_mfma_f32_16x16x32_bf16 v[72:75], v[72:75], v[80:83], v[64:67]
	ds_read_b128 v[96:99], v96
	s_nop 1
	ds_read_b128 v[64:67], v151 offset:128
	s_waitcnt lgkmcnt(1)
	v_mfma_f32_16x16x32_bf16 v[96:99], v[96:99], v[76:79], v[72:75]
	s_nop 2
	v_add_u32_e32 v198, 0x12300, v149
	ds_read_b128 v[198:201], v198
	ds_read_b128 v[100:103], v100
	s_waitcnt lgkmcnt(1)
	v_mfma_f32_16x16x32_bf16 v[72:75], v[198:201], v[80:83], v[60:63]
	v_add_u32_e32 v228, 0x12c00, v149
	ds_read_b128 v[228:231], v228
	ds_read_b128 v[104:107], v104
	ds_read_b128 v[60:63], v151 offset:192
	s_waitcnt lgkmcnt(3)
	v_mfma_f32_16x16x32_bf16 v[100:103], v[100:103], v[76:79], v[72:75]
	s_waitcnt lgkmcnt(2)
	v_mfma_f32_16x16x32_bf16 v[72:75], v[228:231], v[80:83], v[56:59]
	v_add_u32_e32 v198, 0x13500, v149
	ds_read_b128 v[198:201], v198
	ds_read_b128 v[108:111], v108
	ds_read_b128 v[56:59], v151 offset:256
	s_waitcnt lgkmcnt(4)
	v_mfma_f32_16x16x32_bf16 v[104:107], v[104:107], v[76:79], v[72:75]
	s_waitcnt lgkmcnt(2)
	v_mfma_f32_16x16x32_bf16 v[72:75], v[198:201], v[80:83], v[52:55]
	v_add_u32_e32 v228, 0x13e00, v149
	ds_read_b128 v[228:231], v228
	ds_read_b128 v[112:115], v112
	ds_read_b128 v[52:55], v151 offset:320
	s_waitcnt lgkmcnt(4)
	v_mfma_f32_16x16x32_bf16 v[108:111], v[108:111], v[76:79], v[72:75]
	s_waitcnt lgkmcnt(2)
	v_mfma_f32_16x16x32_bf16 v[72:75], v[228:231], v[80:83], v[48:51]
	v_add_u32_e32 v198, 0x14700, v149
	ds_read_b128 v[198:201], v198
	ds_read_b128 v[116:119], v116
	ds_read_b128 v[48:51], v151 offset:384
	s_waitcnt lgkmcnt(4)
	v_mfma_f32_16x16x32_bf16 v[112:115], v[112:115], v[76:79], v[72:75]
	s_waitcnt lgkmcnt(2)
	v_mfma_f32_16x16x32_bf16 v[72:75], v[198:201], v[80:83], v[44:47]
	v_add_u32_e32 v228, 0x15000, v149
	ds_read_b128 v[228:231], v228
	ds_read_b128 v[120:123], v120
	ds_read_b128 v[44:47], v151 offset:448
	s_waitcnt lgkmcnt(4)
	v_mfma_f32_16x16x32_bf16 v[116:119], v[116:119], v[76:79], v[72:75]
	s_waitcnt lgkmcnt(2)
	v_mfma_f32_16x16x32_bf16 v[72:75], v[228:231], v[80:83], v[40:43]
	v_add_u32_e32 v198, 0x15900, v149
	ds_read_b128 v[198:201], v198
	ds_read_b128 v[124:127], v124
	ds_read_b128 v[40:43], v151 offset:512
	s_waitcnt lgkmcnt(4)
	v_mfma_f32_16x16x32_bf16 v[120:123], v[120:123], v[76:79], v[72:75]
	s_waitcnt lgkmcnt(2)
	v_mfma_f32_16x16x32_bf16 v[72:75], v[198:201], v[80:83], v[36:39]
	v_add_u32_e32 v228, 0x16200, v149
	ds_read_b128 v[228:231], v228
	ds_read_b128 v[128:131], v128
	ds_read_b128 v[36:39], v151 offset:576
	s_waitcnt lgkmcnt(4)
	v_mfma_f32_16x16x32_bf16 v[124:127], v[124:127], v[76:79], v[72:75]
	s_waitcnt lgkmcnt(2)
	v_mfma_f32_16x16x32_bf16 v[72:75], v[228:231], v[80:83], v[32:35]
	v_add_u32_e32 v198, 0x16b00, v149
	ds_read_b128 v[198:201], v198
	ds_read_b128 v[132:135], v132
	ds_read_b128 v[32:35], v151 offset:640
	s_waitcnt lgkmcnt(4)
	v_mfma_f32_16x16x32_bf16 v[128:131], v[128:131], v[76:79], v[72:75]
	s_waitcnt lgkmcnt(2)
	v_mfma_f32_16x16x32_bf16 v[72:75], v[198:201], v[80:83], v[28:31]
	v_add_u32_e32 v228, 0x17400, v149
	ds_read_b128 v[228:231], v228
	ds_read_b128 v[136:139], v136
	ds_read_b128 v[28:31], v151 offset:704
	s_waitcnt lgkmcnt(4)
	v_mfma_f32_16x16x32_bf16 v[132:135], v[132:135], v[76:79], v[72:75]
	s_waitcnt lgkmcnt(2)
	v_mfma_f32_16x16x32_bf16 v[72:75], v[228:231], v[80:83], v[24:27]
	v_add_u32_e32 v198, 0x17d00, v149
	ds_read_b128 v[198:201], v198
	ds_read_b128 v[140:143], v140
	ds_read_b128 v[24:27], v151 offset:768
	s_waitcnt lgkmcnt(4)
	v_mfma_f32_16x16x32_bf16 v[136:139], v[136:139], v[76:79], v[72:75]
	s_waitcnt lgkmcnt(2)
	v_mfma_f32_16x16x32_bf16 v[72:75], v[198:201], v[80:83], v[20:23]
	v_add_u32_e32 v228, 0x18600, v149
	ds_read_b128 v[228:231], v228
	ds_read_b128 v[144:147], v144
	ds_read_b128 v[20:23], v151 offset:832
	s_waitcnt lgkmcnt(4)
	v_mfma_f32_16x16x32_bf16 v[140:143], v[140:143], v[76:79], v[72:75]
	s_waitcnt lgkmcnt(2)
	v_mfma_f32_16x16x32_bf16 v[72:75], v[228:231], v[80:83], v[16:19]
	s_nop 2
	ds_read_b128 v[16:19], v151 offset:896
	s_waitcnt lgkmcnt(2)
	v_mfma_f32_16x16x32_bf16 v[144:147], v[144:147], v[76:79], v[72:75]
	s_nop 2
	v_add_u32_e32 v72, 0x18f00, v149
	ds_read_b128 v[72:75], v72
	v_add_u32_e32 v149, 0x18f40, v149
	s_waitcnt lgkmcnt(0)
	v_mfma_f32_16x16x32_bf16 v[72:75], v[72:75], v[80:83], v[4:7]
	ds_read_b128 v[80:83], v149
	s_nop 1
	ds_read_b128 v[4:7], v151 offset:960
	s_waitcnt lgkmcnt(0)
	v_mfma_f32_16x16x32_bf16 v[76:79], v[80:83], v[76:79], v[72:75]
	s_barrier
	s_cbranch_vccnz .LBB0_805
	s_nop 0
	v_mov_b32_e32 v72, v173
	v_add_u32_e32 v196, s62, v211
	v_add_u32_e32 v80, 0, v72
	ds_read_b128 v[72:75], v80
	ds_read_b128 v[80:83], v80 offset:8704
	v_ashrrev_i32_e32 v197, 31, v196
	v_lshlrev_b64 v[196:197], 12, v[196:197]
	v_lshl_add_u64 v[196:197], v[156:157], 0, v[196:197]
	s_waitcnt lgkmcnt(1)
	global_store_dwordx4 v[196:197], v[72:75], off
	s_nop 1
	v_lshl_add_u64 v[72:73], v[196:197], 0, s[40:41]
	s_waitcnt lgkmcnt(0)
	global_store_dwordx4 v[72:73], v[80:83], off
	s_branch .LBB0_805
